# stack2 + attention phase: static s_setprio 1 for the later-dispatched half (waves 4-7), reset at phase exit, run 1
# speedup vs baseline: 1.0107x; 1.0107x over previous
; #define LAS __attribute__((address_space(3)))
; #define KA() ([]() __attribute__((always_inline)) { KArgs p_ = (KArgs)__builtin_amdgcn_kernarg_segment_ptr(); asm volatile("" : "+s"(p_)); return p_; }())
; #define PH_IDS() int tid = TID_NOW(); asm volatile("" : "+v"(tid)); const int lane = tid & 63, wave = __builtin_amdgcn_readfirstlane(tid >> 6); int bx = blockIdx.x; asm volatile("" : "+s"(bx)); \
;     const int G = gridDim.x, vcu = (G % 8 == 0) ? (bx % 8) * (G / 8) + bx / 8 : bx, gw = vcu * NWAVES + wave, NGW = G * NWAVES; (void)lane; (void)gw; (void)NGW; (void)vcu
; __global__ void __launch_bounds__(NWAVES * 64, 2) hymba_fwd(Args args_unused) {
;     ...
;         {
;             KArgs A = KA(); PH_IDS(); unsigned char* ws = A->ws;
;             const float lam_init = 0.8f - 0.6f * __expf(-0.3f * (float)l);
;             const float e1 = __expf(wave_sum(IN_F(A, 5)[l * 64 + lane] * IN_F(A, 6)[l * 64 + lane])), e2 = __expf(wave_sum(IN_F(A, 7)[l * 64 + lane] * IN_F(A, 8)[l * 64 + lane]));
;             const float lam = __uint_as_float((unsigned)__builtin_amdgcn_readfirstlane((int)__float_as_uint(e1 - e2 + lam_init))), osc = __uint_as_float((unsigned)__builtin_amdgcn_readfirstlane((int)__float_as_uint(1.0f - lam_init)));
;             const float* gsub = IN_F(A, 9) + l * 128;
;             unsigned* qcnt = (unsigned*)(ws + WS_CTL) + 64 * (1 + 8 * l);
;             volatile LAS unsigned* qs = (volatile LAS unsigned*)(ldsl + MISC_OFF) + 16;
;             const attn_body::bf16* Qb = (const attn_body::bf16*)(ws + WS_QKV);
.LBB0_231:
	s_or_b64 exec, exec, s[4:5]
	s_mov_b64 s[8:9], s[84:85]
	s_mov_b32 s0, -1
	s_waitcnt lgkmcnt(0)
	s_barrier
	s_mov_b32 s21, s82
	v_mbcnt_lo_u32_b32 v0, s0, 0
	v_mbcnt_hi_u32_b32 v0, s0, v0
	v_or_b32_e32 v247, s83, v0
	s_cmp_ge_u32 s83, 0x100
	s_cbranch_scc0 .Lattn_prio_old
	s_setprio 1
.Lattn_prio_old:
	s_load_dwordx8 s[0:7], s[8:9], 0x28
	s_lshl_b32 s10, s26, 6
	v_and_or_b32 v0, v247, 63, s10
	v_lshlrev_b64 v[2:3], 2, v[0:1]
	s_lshl_b32 s38, s26, 7
	s_waitcnt lgkmcnt(0)
	v_lshl_add_u64 v[4:5], s[0:1], 0, v[2:3]
	global_load_dword v0, v[4:5], off
	v_lshl_add_u64 v[4:5], s[2:3], 0, v[2:3]
	global_load_dword v6, v[4:5], off
	v_lshl_add_u64 v[4:5], s[4:5], 0, v[2:3]
	v_lshl_add_u64 v[2:3], s[6:7], 0, v[2:3]
	global_load_dword v4, v[4:5], off
	s_xor_b64 s[66:67], s[22:23], -1
	global_load_dword v2, v[2:3], off
	v_cvt_f32_u32_e32 v3, s26
	s_load_dwordx2 s[4:5], s[8:9], 0x90
	s_load_dwordx2 s[0:1], s[8:9], 0x48
	s_lshl_b64 s[2:3], s[38:39], 2
	v_mov_b32_e32 v5, 0x3f4ccccd
	v_mul_f32_e32 v3, 0xbe99999a, v3
	v_mul_f32_e32 v3, 0x3fb8aa3b, v3
	v_exp_f32_e32 v3, v3
	s_waitcnt lgkmcnt(0)
	s_add_u32 s10, s0, s2
	s_addc_u32 s11, s1, s3
	s_lshl_b32 s38, s26, 9
	v_fmamk_f32 v3, v3, 0xbf19999a, v5
	s_mov_b32 s84, 0
	v_readfirstlane_b32 s0, v3
	v_cmp_eq_u32_e64 s[8:9], 0, v247
	s_waitcnt vmcnt(2)
	v_mul_f32_e32 v5, v0, v6
	v_sub_f32_e64 v244, 1.0, s0
	s_lshl_b64 s[0:1], s[38:39], 2
	s_add_u32 s12, s4, s0
	s_addc_u32 s13, s5, s1
	s_waitcnt vmcnt(0)
	v_mul_f32_e32 v7, v4, v2
	s_add_u32 s85, s4, 0x7800000
	v_mov_b32_dpp v5, v5 quad_perm:[1,0,3,2] row_mask:0xf bank_mask:0xf bound_ctrl:1
	v_mov_b32_dpp v7, v7 quad_perm:[1,0,3,2] row_mask:0xf bank_mask:0xf bound_ctrl:1
	s_addc_u32 s86, s5, 0
	v_fmac_f32_e32 v5, v0, v6
	v_fmac_f32_e32 v7, v4, v2
	s_add_u32 s0, s4, 0x7800c00
	v_add_f32_dpp v0, v5, v5 quad_perm:[2,3,0,1] row_mask:0xf bank_mask:0xf bound_ctrl:1
	v_add_f32_dpp v2, v7, v7 quad_perm:[2,3,0,1] row_mask:0xf bank_mask:0xf bound_ctrl:1
	v_writelane_b32 v255, s0, 17
	s_addc_u32 s0, s5, 0
	v_add_f32_dpp v0, v0, v0 row_ror:4 row_mask:0xf bank_mask:0xf bound_ctrl:1
	v_add_f32_dpp v2, v2, v2 row_ror:4 row_mask:0xf bank_mask:0xf bound_ctrl:1
	v_writelane_b32 v255, s0, 18
	s_add_u32 s0, s4, 0x7801000
	v_add_f32_dpp v0, v0, v0 row_ror:8 row_mask:0xf bank_mask:0xf bound_ctrl:1
	v_add_f32_dpp v2, v2, v2 row_ror:8 row_mask:0xf bank_mask:0xf bound_ctrl:1
	v_writelane_b32 v255, s0, 19
	s_addc_u32 s0, s5, 0
	v_mov_b32_e32 v4, v0
	v_mov_b32_e32 v5, v2
	s_add_u32 s91, s4, 0x7801400
	v_permlane16_swap_b32_e32 v0, v4
	v_permlane16_swap_b32_e32 v2, v5
	s_addc_u32 s92, s5, 0
	v_add_f32_e32 v0, v0, v4
	v_add_f32_e32 v2, v2, v5
	s_add_u32 s93, s4, 0x17800400
	v_mov_b32_e32 v4, v0
	v_mov_b32_e32 v5, v2
	s_addc_u32 s94, s5, 0
	v_permlane32_swap_b32_e32 v0, v4
	v_permlane32_swap_b32_e32 v2, v5
	s_add_u32 s95, s4, 0x400000
	v_add_f32_e32 v0, v0, v4
	v_add_f32_e32 v2, v2, v5
	s_addc_u32 s36, s5, 0
	v_mul_f32_e32 v0, 0x3fb8aa3b, v0
	v_mul_f32_e32 v2, 0x3fb8aa3b, v2
	s_add_u32 s37, s4, 0x7800400
	v_exp_f32_e32 v0, v0
	v_exp_f32_e32 v2, v2
	s_addc_u32 s3, s5, 0
	s_add_u32 s2, s4, 0x7800800
	s_addc_u32 s20, s5, 0
	s_add_u32 s42, s4, 0x17800000
	v_sub_f32_e32 v0, v0, v2
	s_addc_u32 s43, s5, 0
	v_add_f32_e32 v0, v3, v0
	v_writelane_b32 v255, s0, 20
	s_add_u32 s0, s4, 0x13800000
	v_readfirstlane_b32 s14, v0
	s_addc_u32 s1, s5, 0
	s_mov_b32 s15, s14
	s_branch .LBB0_233

; __device__ __forceinline__ unsigned xb_add(unsigned* p, unsigned v) { return __hip_atomic_fetch_add(p, v, __ATOMIC_RELAXED, __HIP_MEMORY_SCOPE_AGENT); }
; __device__ __forceinline__ void xcd_barrier(const XcdBarrier& b, const int tid_in) {
;     asm volatile("s_waitcnt vmcnt(0)" ::: "memory");
;     __syncthreads();
;     if (tid_in == 0) {
;         unsigned* bar = b.bar;
;         __builtin_amdgcn_s_waitcnt(0);
;         unsigned nloc = b.st[0], nx = b.st[1];
;         if (nloc == 0u) { xcd_barrier_complete(bar, b.x, nloc, nx); b.st[0] = nloc; b.st[1] = nx; }
;         const unsigned old = xb_add(&bar[XB_XSUB(b.x)], 1u);
;         const unsigned gen = old / nloc;
;         if (old + 1u == (gen + 1u) * nloc) {
.LBB0_415:
	s_setprio 0
	v_readlane_b32 s84, v255, 12
	v_readlane_b32 s85, v255, 13
	s_mov_b64 s[6:7], s[84:85]
	s_mov_b32 s1, -1
	s_getreg_b32 s0, hwreg(HW_REG_XCC_ID, 0, 4)
	v_readlane_b32 s83, v255, 14
	v_mbcnt_lo_u32_b32 v0, s1, 0
	v_mbcnt_hi_u32_b32 v0, s1, v0
	v_or_b32_e32 v0, s83, v0
	s_waitcnt vmcnt(0)
	s_barrier
	v_cmp_eq_u32_e32 vcc, 0, v0
	s_mov_b64 s[4:5], exec
	v_readlane_b32 s74, v255, 3
	v_readlane_b32 s78, v255, 5
	s_and_b64 s[2:3], s[4:5], vcc
	v_readlane_b32 s82, v255, 11
	v_readlane_b32 s75, v255, 4
	v_readlane_b32 s79, v255, 6
	s_movk_i32 s86, 0xc1
	s_mov_b64 s[80:81], 0x40000
	s_mov_b32 s77, 0x40000
	s_mov_b64 s[88:89], 0x48000
	s_mov_b32 s87, 0x48000
	s_mov_b64 s[90:91], 0x50000
	s_mov_b32 s94, 0x50000
	s_mov_b64 s[92:93], 0x58000
	s_mov_b32 s95, 0x58000
	v_readlane_b32 s26, v255, 15
	v_mov_b32_e32 v234, 0x2000
	v_mov_b32_e32 v235, 1
	v_mov_b64_e32 v[236:237], 0x5ff
	v_mov_b32_e32 v238, 0x3e38aa3b
	v_mov_b64_e32 v[232:233], 0x200
	v_mov_b64_e32 v[240:241], 0x1ff
	v_mov_b64_e32 v[242:243], 0xb00
	v_mov_b64_e32 v[244:245], 0xaff
	v_readlane_b32 s27, v255, 16
	s_mov_b64 exec, s[2:3]
	s_cbranch_execz .LBB0_468
	v_readlane_b32 s1, v255, 7
	s_load_dwordx2 s[6:7], s[6:7], 0x90
	s_waitcnt vmcnt(0) expcnt(0) lgkmcnt(0)
	v_mov_b32_e32 v0, s1
	ds_read_b32 v3, v0
	v_readlane_b32 s1, v255, 8
	s_and_b32 s0, s0, 15
	s_waitcnt lgkmcnt(0)
	v_cmp_ne_u32_e32 vcc, 0, v3
	v_mov_b32_e32 v0, s1
	ds_read_b32 v0, v0
	s_cbranch_vccnz .LBB0_432
	s_add_u32 s8, s6, 0x4200
	s_addc_u32 s9, s7, 0
	s_add_u32 s10, s6, 0x4400
	s_addc_u32 s11, s7, 0
	s_add_u32 s12, s6, 0x4500
	s_addc_u32 s13, s7, 0
	s_add_u32 s14, s6, 0x4600
	s_addc_u32 s15, s7, 0
	s_add_u32 s16, s6, 0x4700
	s_addc_u32 s17, s7, 0
	s_add_u32 s18, s6, 0x4800
	s_addc_u32 s19, s7, 0
	s_add_u32 s22, s6, 0x4900
	s_addc_u32 s23, s7, 0
	s_add_u32 s68, s6, 0x4a00
	s_addc_u32 s69, s7, 0
	s_add_u32 s70, s6, 0x4b00
	s_addc_u32 s71, s7, 0
	s_add_u32 s72, s6, 0x4c00
	s_addc_u32 s73, s7, 0
	s_add_u32 s74, s6, 0x4d00
	s_addc_u32 s75, s7, 0
	s_add_u32 s76, s6, 0x4e00
	s_addc_u32 s77, s7, 0
	s_add_u32 s78, s6, 0x4f00
	s_addc_u32 s79, s7, 0
	s_add_u32 s80, s6, 0x5000
	s_addc_u32 s81, s7, 0
	s_add_u32 s82, s6, 0x5100
	s_addc_u32 s83, s7, 0
	s_add_u32 s84, s6, 0x5200
	s_addc_u32 s85, s7, 0
	s_add_u32 s86, s6, 0x5300
	s_addc_u32 s87, s7, 0
	s_mov_b32 s1, 1
	s_branch .LBB0_420
